# stacked: gate_a GEMM epilogue loads batched, per-four-steps gate fetch in U sweep, token B re-uses token A's gain registers (14 fewer loads per pair)
# speedup vs baseline: 1.0030x; 1.0030x over previous
; __device__ __forceinline__ unsigned cvt_pk_bf16(float lo, float hi) { unsigned r; asm volatile("v_cvt_pk_bf16_f32 %0, %1, %2" : "=v"(r) : "v"(lo), "v"(hi)); return r; }
; __device__ __forceinline__ float bflo(unsigned w) { return __uint_as_float(w << 16); }
; __device__ __forceinline__ float bfhi(unsigned w) { return __uint_as_float(w & 0xffff0000u); }
; __device__ void ph_peer(const float* __restrict__ SC, const bf16_t* __restrict__ H  , const float* __restrict__ gffn, const unsigned char* __restrict__ U, const unsigned char* __restrict__ V, float* X, const float* __restrict__ fgain) {
;     ...
;         {   const u32x4* hp = (const u32x4*)(H + (size_t)tok * 1024 + 64 * sub);
; #pragma unroll
;             for (int q = 0; q < 8; ++q) { const u32x4 w = hp[q];
;                 const float4 ga = *(const float4*)(gffn + 64 * sub + q * 8), gb = *(const float4*)(gffn + 64 * sub + q * 8 + 4);
;                 hf2[q * 4 + 0] = cvt_pk_bf16(bflo(w.x) * rstd * ga.x, bfhi(w.x) * rstd * ga.y);
;                 hf2[q * 4 + 1] = cvt_pk_bf16(bflo(w.y) * rstd * ga.z, bfhi(w.y) * rstd * ga.w);
;                 hf2[q * 4 + 2] = cvt_pk_bf16(bflo(w.z) * rstd * gb.x, bfhi(w.z) * rstd * gb.y);
;                 hf2[q * 4 + 3] = cvt_pk_bf16(bflo(w.w) * rstd * gb.z, bfhi(w.w) * rstd * gb.w); } }
.LBB0_230:
	s_waitcnt vmcnt(0) lgkmcnt(0)
	v_lshlrev_b32_e32 v2, 16, v180
	v_and_b32_e32 v3, 0xffff0000, v180
	v_lshlrev_b32_e32 v4, 16, v181
	v_and_b32_e32 v5, 0xffff0000, v181
	v_pk_mul_f32 v[2:3], v[2:3], v[12:13] op_sel_hi:[1,0]
	v_pk_mul_f32 v[4:5], v[4:5], v[12:13] op_sel_hi:[1,0]
	v_pk_mul_f32 v[2:3], v[2:3], v[64:65]
	v_pk_mul_f32 v[4:5], v[4:5], v[66:67]
	v_cvt_pk_bf16_f32 v95, v2, v3
	v_cvt_pk_bf16_f32 v159, v4, v5
	v_lshlrev_b32_e32 v2, 16, v182
	v_and_b32_e32 v3, 0xffff0000, v182
	v_lshlrev_b32_e32 v4, 16, v183
	v_and_b32_e32 v5, 0xffff0000, v183
	v_pk_mul_f32 v[2:3], v[2:3], v[12:13] op_sel_hi:[1,0]
	v_pk_mul_f32 v[4:5], v[4:5], v[12:13] op_sel_hi:[1,0]
	v_pk_mul_f32 v[2:3], v[2:3], v[68:69]
	v_pk_mul_f32 v[4:5], v[4:5], v[70:71]
	v_cvt_pk_bf16_f32 v160, v2, v3
	v_cvt_pk_bf16_f32 v161, v4, v5
	v_lshlrev_b32_e32 v2, 16, v184
	v_and_b32_e32 v3, 0xffff0000, v184
	v_lshlrev_b32_e32 v4, 16, v185
	v_and_b32_e32 v5, 0xffff0000, v185
	v_pk_mul_f32 v[2:3], v[2:3], v[12:13] op_sel_hi:[1,0]
	v_pk_mul_f32 v[4:5], v[4:5], v[12:13] op_sel_hi:[1,0]
	v_pk_mul_f32 v[2:3], v[2:3], v[32:33]
	v_pk_mul_f32 v[4:5], v[4:5], v[34:35]
	v_cvt_pk_bf16_f32 v180, v2, v3
	v_cvt_pk_bf16_f32 v181, v4, v5
	v_lshlrev_b32_e32 v2, 16, v186
	v_and_b32_e32 v3, 0xffff0000, v186
	v_lshlrev_b32_e32 v4, 16, v187
	v_and_b32_e32 v5, 0xffff0000, v187
	v_pk_mul_f32 v[2:3], v[2:3], v[12:13] op_sel_hi:[1,0]
	v_pk_mul_f32 v[4:5], v[4:5], v[12:13] op_sel_hi:[1,0]
	v_pk_mul_f32 v[2:3], v[2:3], v[36:37]
	v_pk_mul_f32 v[4:5], v[4:5], v[38:39]
	v_cvt_pk_bf16_f32 v182, v2, v3
	v_cvt_pk_bf16_f32 v183, v4, v5
	v_lshlrev_b32_e32 v2, 16, v188
	v_and_b32_e32 v3, 0xffff0000, v188
	v_lshlrev_b32_e32 v4, 16, v189
	v_and_b32_e32 v5, 0xffff0000, v189
	v_pk_mul_f32 v[2:3], v[2:3], v[12:13] op_sel_hi:[1,0]
	v_pk_mul_f32 v[4:5], v[4:5], v[12:13] op_sel_hi:[1,0]
	v_pk_mul_f32 v[2:3], v[2:3], v[40:41]
	v_pk_mul_f32 v[4:5], v[4:5], v[42:43]
	v_cvt_pk_bf16_f32 v184, v2, v3
	v_cvt_pk_bf16_f32 v185, v4, v5
	v_lshlrev_b32_e32 v2, 16, v190
	v_and_b32_e32 v3, 0xffff0000, v190
	v_lshlrev_b32_e32 v4, 16, v191
	v_and_b32_e32 v5, 0xffff0000, v191
	v_pk_mul_f32 v[2:3], v[2:3], v[12:13] op_sel_hi:[1,0]
	v_pk_mul_f32 v[4:5], v[4:5], v[12:13] op_sel_hi:[1,0]
	v_pk_mul_f32 v[2:3], v[2:3], v[44:45]
	v_pk_mul_f32 v[4:5], v[4:5], v[46:47]
	v_cvt_pk_bf16_f32 v186, v2, v3
	v_cvt_pk_bf16_f32 v187, v4, v5
	v_lshlrev_b32_e32 v2, 16, v192
	v_and_b32_e32 v3, 0xffff0000, v192
	v_lshlrev_b32_e32 v4, 16, v193
	v_and_b32_e32 v5, 0xffff0000, v193
	v_pk_mul_f32 v[2:3], v[2:3], v[12:13] op_sel_hi:[1,0]
	v_pk_mul_f32 v[4:5], v[4:5], v[12:13] op_sel_hi:[1,0]
	v_pk_mul_f32 v[2:3], v[2:3], v[48:49]
	v_pk_mul_f32 v[4:5], v[4:5], v[50:51]
	v_cvt_pk_bf16_f32 v188, v2, v3
	v_cvt_pk_bf16_f32 v189, v4, v5
	v_lshlrev_b32_e32 v2, 16, v194
	v_and_b32_e32 v3, 0xffff0000, v194
	v_lshlrev_b32_e32 v4, 16, v195
	v_and_b32_e32 v5, 0xffff0000, v195
	v_pk_mul_f32 v[2:3], v[2:3], v[12:13] op_sel_hi:[1,0]
	v_pk_mul_f32 v[4:5], v[4:5], v[12:13] op_sel_hi:[1,0]
	v_pk_mul_f32 v[2:3], v[2:3], v[52:53]
	v_pk_mul_f32 v[4:5], v[4:5], v[54:55]
	v_cvt_pk_bf16_f32 v190, v2, v3
	v_cvt_pk_bf16_f32 v191, v4, v5
	v_lshlrev_b32_e32 v2, 16, v196
	v_and_b32_e32 v3, 0xffff0000, v196
	v_lshlrev_b32_e32 v4, 16, v197
	v_and_b32_e32 v5, 0xffff0000, v197
	v_pk_mul_f32 v[2:3], v[2:3], v[12:13] op_sel_hi:[1,0]
	v_pk_mul_f32 v[4:5], v[4:5], v[12:13] op_sel_hi:[1,0]
	v_pk_mul_f32 v[2:3], v[2:3], v[56:57]
	v_pk_mul_f32 v[4:5], v[4:5], v[58:59]
	v_cvt_pk_bf16_f32 v192, v2, v3
	v_cvt_pk_bf16_f32 v193, v4, v5
	v_lshlrev_b32_e32 v2, 16, v198
	v_and_b32_e32 v3, 0xffff0000, v198
	v_lshlrev_b32_e32 v4, 16, v199
	v_and_b32_e32 v5, 0xffff0000, v199
	v_pk_mul_f32 v[2:3], v[2:3], v[12:13] op_sel_hi:[1,0]
	v_pk_mul_f32 v[4:5], v[4:5], v[12:13] op_sel_hi:[1,0]
	v_pk_mul_f32 v[2:3], v[2:3], v[60:61]
	v_pk_mul_f32 v[4:5], v[4:5], v[62:63]
	v_cvt_pk_bf16_f32 v194, v2, v3
	v_cvt_pk_bf16_f32 v195, v4, v5
	v_lshlrev_b32_e32 v2, 16, v200
	v_and_b32_e32 v3, 0xffff0000, v200
	v_lshlrev_b32_e32 v4, 16, v201
	v_and_b32_e32 v5, 0xffff0000, v201
	v_pk_mul_f32 v[2:3], v[2:3], v[12:13] op_sel_hi:[1,0]
	v_pk_mul_f32 v[4:5], v[4:5], v[12:13] op_sel_hi:[1,0]
	v_pk_mul_f32 v[2:3], v[2:3], v[98:99]
	v_pk_mul_f32 v[4:5], v[4:5], v[100:101]
	v_cvt_pk_bf16_f32 v196, v2, v3
	v_cvt_pk_bf16_f32 v197, v4, v5
	v_lshlrev_b32_e32 v2, 16, v202
	v_and_b32_e32 v3, 0xffff0000, v202
	v_lshlrev_b32_e32 v4, 16, v203
	v_and_b32_e32 v5, 0xffff0000, v203
	v_pk_mul_f32 v[2:3], v[2:3], v[12:13] op_sel_hi:[1,0]
	v_pk_mul_f32 v[4:5], v[4:5], v[12:13] op_sel_hi:[1,0]
	v_pk_mul_f32 v[2:3], v[2:3], v[102:103]
	v_pk_mul_f32 v[4:5], v[4:5], v[104:105]
	v_cvt_pk_bf16_f32 v198, v2, v3
	v_cvt_pk_bf16_f32 v199, v4, v5
	v_lshlrev_b32_e32 v2, 16, v204
	v_and_b32_e32 v3, 0xffff0000, v204
; __device__ __forceinline__ float bflo(unsigned w) { return __uint_as_float(w << 16); }
; __device__ __forceinline__ float bfhi(unsigned w) { return __uint_as_float(w & 0xffff0000u); }
; __device__ void ph_peer(const float* __restrict__ SC, const bf16_t* __restrict__ H  , const float* __restrict__ gffn, const unsigned char* __restrict__ U, const unsigned char* __restrict__ V, float* X, const float* __restrict__ fgain) {
;     ...
;         {   const u32x4* hp0 = (const u32x4*)(H + (size_t)tok * 1024); float ss = 0.f;
; #pragma unroll
;             for (int s4 = 0; s4 < 2; ++s4) { const u32x4 w = hp0[s4 * 64 + lane]; const unsigned ww[4] = {w.x, w.y, w.z, w.w};
; #pragma unroll
;                 for (int e4 = 0; e4 < 4; ++e4) { const float lo = bflo(ww[e4]), hi = bfhi(ww[e4]); ss += lo * lo + hi * hi; } }
;             ss = wave_sum(ss); rstd = rsqrtf(ss * (1.0f / 1024.0f) + 1e-6f); }
;     ...
;         {   const u32x4* hp = (const u32x4*)(H + (size_t)tok * 1024 + 64 * sub);
; #pragma unroll
;             for (int q = 0; q < 8; ++q) { const u32x4 w = hp[q];
;                 const float4 ga = *(const float4*)(gffn + 64 * sub + q * 8), gb = *(const float4*)(gffn + 64 * sub + q * 8 + 4);
	v_lshlrev_b32_e32 v4, 16, v205
	v_and_b32_e32 v5, 0xffff0000, v205
	v_pk_mul_f32 v[2:3], v[2:3], v[12:13] op_sel_hi:[1,0]
	v_pk_mul_f32 v[4:5], v[4:5], v[12:13] op_sel_hi:[1,0]
	v_pk_mul_f32 v[2:3], v[2:3], v[106:107]
	v_pk_mul_f32 v[4:5], v[4:5], v[108:109]
	v_cvt_pk_bf16_f32 v200, v2, v3
	v_cvt_pk_bf16_f32 v201, v4, v5
	v_lshlrev_b32_e32 v2, 16, v206
	v_and_b32_e32 v3, 0xffff0000, v206
	v_lshlrev_b32_e32 v4, 16, v207
	v_and_b32_e32 v5, 0xffff0000, v207
	v_pk_mul_f32 v[2:3], v[2:3], v[12:13] op_sel_hi:[1,0]
	v_pk_mul_f32 v[4:5], v[4:5], v[12:13] op_sel_hi:[1,0]
	v_pk_mul_f32 v[2:3], v[2:3], v[110:111]
	v_pk_mul_f32 v[4:5], v[4:5], v[112:113]
	v_cvt_pk_bf16_f32 v202, v2, v3
	v_cvt_pk_bf16_f32 v203, v4, v5
	v_lshlrev_b32_e32 v2, 16, v208
	v_and_b32_e32 v3, 0xffff0000, v208
	v_lshlrev_b32_e32 v4, 16, v209
	v_and_b32_e32 v5, 0xffff0000, v209
	v_pk_mul_f32 v[2:3], v[2:3], v[12:13] op_sel_hi:[1,0]
	v_pk_mul_f32 v[4:5], v[4:5], v[12:13] op_sel_hi:[1,0]
	v_pk_mul_f32 v[2:3], v[2:3], v[114:115]
	v_pk_mul_f32 v[4:5], v[4:5], v[116:117]
	v_cvt_pk_bf16_f32 v204, v2, v3
	v_cvt_pk_bf16_f32 v205, v4, v5
	v_lshlrev_b32_e32 v2, 16, v210
	v_and_b32_e32 v3, 0xffff0000, v210
	v_lshlrev_b32_e32 v4, 16, v211
	v_and_b32_e32 v5, 0xffff0000, v211
	v_pk_mul_f32 v[2:3], v[2:3], v[12:13] op_sel_hi:[1,0]
	v_pk_mul_f32 v[4:5], v[4:5], v[12:13] op_sel_hi:[1,0]
	v_pk_mul_f32 v[2:3], v[2:3], v[118:119]
	v_pk_mul_f32 v[4:5], v[4:5], v[120:121]
	v_cvt_pk_bf16_f32 v206, v2, v3
	v_cvt_pk_bf16_f32 v207, v4, v5
	v_readlane_b32 s0, v251, 29
	s_nop 3
	v_add_u32_e32 v72, s0, v72
	v_ashrrev_i32_e32 v73, 31, v72
	v_readlane_b32 s0, v253, 24
	v_lshlrev_b64 v[0:1], 11, v[72:73]
	v_readlane_b32 s1, v253, 25
	v_lshlrev_b64 v[88:89], 10, v[72:73]
	v_mov_b32_e32 v156, 0
	v_lshl_add_u64 v[0:1], s[0:1], 0, v[0:1]
	v_lshl_add_u64 v[6:7], v[0:1], 0, v[128:129]
	global_load_dwordx4 v[2:5], v[6:7], off
	global_load_dwordx4 v[122:125], v[6:7], off offset:1024
	v_add_co_u32_e32 v216, vcc, v0, v94
	s_nop 1
	v_addc_co_u32_e32 v217, vcc, 0, v1, vcc
	global_load_dwordx4 v[218:221], v[216:217], off offset:0
	global_load_dwordx4 v[222:225], v[216:217], off offset:16
	global_load_dwordx4 v[226:229], v[216:217], off offset:32
	global_load_dwordx4 v[230:233], v[216:217], off offset:48
	global_load_dwordx4 v[234:237], v[216:217], off offset:64
	global_load_dwordx4 v[238:241], v[216:217], off offset:80
	global_load_dwordx4 v[242:245], v[216:217], off offset:96
	global_load_dwordx4 v[246:249], v[216:217], off offset:112
	v_mov_b32_e32 v157, 0
	v_mov_b32_e32 v158, 0
	s_waitcnt vmcnt(9)
	v_lshlrev_b32_e32 v8, 16, v2
	v_and_b32_e32 v2, 0xffff0000, v2
	v_mul_f32_e32 v2, v2, v2
	v_fmac_f32_e32 v2, v8, v8
	v_lshlrev_b32_e32 v8, 16, v3
	v_and_b32_e32 v3, 0xffff0000, v3
	v_mul_f32_e32 v3, v3, v3
	v_fmac_f32_e32 v3, v8, v8
	v_add_f32_e32 v8, v2, v3
	v_lshlrev_b32_e32 v3, 16, v5
	v_lshlrev_b32_e32 v2, 16, v4
	v_and_b32_e32 v5, 0xffff0000, v5
	v_and_b32_e32 v4, 0xffff0000, v4
	v_pk_mul_f32 v[4:5], v[4:5], v[4:5]
	s_nop 0
	v_pk_fma_f32 v[2:3], v[2:3], v[2:3], v[4:5]
	s_nop 0
	v_add_f32_e32 v2, v2, v8
	v_add_f32_e32 v8, v3, v2
	s_waitcnt vmcnt(8)
	v_mov_b32_e32 v2, v122
	v_mov_b32_e32 v3, v123
	v_mov_b32_e32 v4, v124
	v_mov_b32_e32 v5, v125
	v_lshlrev_b32_e32 v7, 16, v3
	v_lshlrev_b32_e32 v6, 16, v2
	v_and_b32_e32 v3, 0xffff0000, v3
	v_and_b32_e32 v2, 0xffff0000, v2
	v_pk_mul_f32 v[2:3], v[2:3], v[2:3]
	s_nop 0
	v_pk_fma_f32 v[2:3], v[6:7], v[6:7], v[2:3]
	s_nop 0
	v_add_f32_e32 v2, v2, v8
	v_add_f32_e32 v6, v3, v2
	v_lshlrev_b32_e32 v3, 16, v5
	v_lshlrev_b32_e32 v2, 16, v4
	v_and_b32_e32 v5, 0xffff0000, v5
	v_and_b32_e32 v4, 0xffff0000, v4
	v_pk_mul_f32 v[4:5], v[4:5], v[4:5]
	s_nop 0
	v_pk_fma_f32 v[2:3], v[2:3], v[2:3], v[4:5]
	s_nop 0
	v_add_f32_e32 v2, v2, v6
	v_add_f32_e32 v2, v3, v2
	s_nop 1
	v_add_f32_dpp v2, v2, v2 quad_perm:[1,0,3,2] row_mask:0xf bank_mask:0xf bound_ctrl:1
	s_nop 1
	v_add_f32_dpp v2, v2, v2 quad_perm:[2,3,0,1] row_mask:0xf bank_mask:0xf bound_ctrl:1
	s_nop 1
	v_add_f32_dpp v2, v2, v2 row_half_mirror row_mask:0xf bank_mask:0xf bound_ctrl:1
	s_nop 1
	v_add_f32_dpp v2, v2, v2 row_mirror row_mask:0xf bank_mask:0xf bound_ctrl:1
	s_nop 0
	v_readlane_b32 s2, v2, 16
	v_readlane_b32 s6, v2, 48
	v_readlane_b32 s0, v2, 0
	v_readlane_b32 s1, v2, 32
	v_mov_b32_e32 v2, s2
	v_mov_b32_e32 v3, s6
	v_pk_add_f32 v[2:3], s[0:1], v[2:3]
	s_mov_b32 s0, 0x800000
	v_add_f32_e32 v2, v2, v3
	v_fmamk_f32 v2, v2, 0x3a800000, v170
	v_cmp_gt_f32_e32 vcc, s0, v2
	v_mul_f32_e32 v3, 0x4b800000, v2
	s_mov_b32 s6, 0
	v_cndmask_b32_e32 v2, v2, v3, vcc
	v_rsq_f32_e32 v2, v2
	s_nop 0
	v_mul_f32_e32 v3, 0x45800000, v2
	v_cndmask_b32_e32 v12, v2, v3, vcc
	v_lshlrev_b64 v[2:3], 13, v[72:73]
	v_lshl_add_u64 v[2:3], v[92:93], 0, v[2:3]
	v_mov_b32_e32 v73, 0

; __device__ __forceinline__ float bflo(unsigned w) { return __uint_as_float(w << 16); }
; __device__ __forceinline__ float bfhi(unsigned w) { return __uint_as_float(w & 0xffff0000u); }
;     __device__ __forceinline__ void operator()(const f32x4 (&acc)[2][2][4][2], const pg8::Unit& u, int wr, int wc, int fr, int fq) const {
;         const int row0 = u.pm * 256 + wr * 64 + fr, col0 = u.pn * 256 + wc * 32 + 4 * fq;
; #pragma unroll
;         for (int ai = 0; ai < 2; ++ai)
; #pragma unroll
;             for (int m = 0; m < 4; ++m) { const size_t r = (size_t)(row0 + ai * 128 + m * 16);
; #pragma unroll
;                 for (int bj = 0; bj < 2; ++bj)
; #pragma unroll
;                     for (int n = 0; n < 2; ++n) { const int c = col0 + bj * 128 + n * 16;
;                         const u32x2 g = *(const u32x2*)(PROJ + r * 8192 + 6144 + c);
;                         const f32x4 s = (f32x4){bflo(g.x), bfhi(g.x), bflo(g.y), bfhi(g.y)};
;                         *(f32x4*)(MT + r * 1024 + c) = acc[ai][bj][m][n] * s; } }
.LBB0_328:
	v_lshl_add_u32 v150, s15, 8, v158
	v_lshl_or_b32 v156, s14, 8, v160
	s_mov_b64 s[14:15], 0x3000
	v_readlane_b32 s6, v251, 26
	v_readlane_b32 s7, v251, 27
	v_lshlrev_b32_e32 v220, 14, v150
	v_lshl_add_u32 v220, v156, 1, v220
	v_add_u32_e32 v220, 0x3000, v220
	v_lshlrev_b32_e32 v221, 12, v150
	v_lshl_add_u32 v221, v156, 2, v221
	v_mov_b32_e32 v216, v220
	v_mov_b32_e32 v218, v221
	v_add_u32_e32 v217, 0x40000, v220
	v_add_u32_e32 v219, 0x10000, v221
	global_load_dwordx2 v[184:185], v216, s[82:83] offset:0
	global_load_dwordx2 v[186:187], v216, s[82:83] offset:32
	global_load_dwordx2 v[188:189], v216, s[82:83] offset:256
	global_load_dwordx2 v[190:191], v216, s[82:83] offset:288
	global_load_dwordx2 v[192:193], v217, s[82:83] offset:0
	global_load_dwordx2 v[194:195], v217, s[82:83] offset:32
	global_load_dwordx2 v[196:197], v217, s[82:83] offset:256
	global_load_dwordx2 v[198:199], v217, s[82:83] offset:288
	s_waitcnt vmcnt(7)
	v_lshlrev_b32_e32 v200, 16, v184
	v_and_b32_e32 v201, 0xffff0000, v184
	v_lshlrev_b32_e32 v202, 16, v185
	v_and_b32_e32 v203, 0xffff0000, v185
	v_pk_mul_f32 v[126:127], v[126:127], v[202:203]
	v_pk_mul_f32 v[124:125], v[124:125], v[200:201]
	global_store_dwordx4 v218, v[124:127], s[6:7] offset:0
	s_waitcnt vmcnt(7)
	v_lshlrev_b32_e32 v204, 16, v186
	v_and_b32_e32 v205, 0xffff0000, v186
	v_lshlrev_b32_e32 v206, 16, v187
	v_and_b32_e32 v207, 0xffff0000, v187
	v_pk_mul_f32 v[122:123], v[122:123], v[206:207]
	v_pk_mul_f32 v[120:121], v[120:121], v[204:205]
	global_store_dwordx4 v218, v[120:123], s[6:7] offset:64
	s_waitcnt vmcnt(7)
	v_lshlrev_b32_e32 v200, 16, v188
	v_and_b32_e32 v201, 0xffff0000, v188
	v_lshlrev_b32_e32 v202, 16, v189
	v_and_b32_e32 v203, 0xffff0000, v189
	v_pk_mul_f32 v[118:119], v[118:119], v[202:203]
	v_pk_mul_f32 v[116:117], v[116:117], v[200:201]
	global_store_dwordx4 v218, v[116:119], s[6:7] offset:512
	s_waitcnt vmcnt(7)
	v_lshlrev_b32_e32 v204, 16, v190
	v_and_b32_e32 v205, 0xffff0000, v190
	v_lshlrev_b32_e32 v206, 16, v191
	v_and_b32_e32 v207, 0xffff0000, v191
	v_pk_mul_f32 v[114:115], v[114:115], v[206:207]
	v_pk_mul_f32 v[112:113], v[112:113], v[204:205]
	global_store_dwordx4 v218, v[112:115], s[6:7] offset:576
	s_waitcnt vmcnt(7)
	v_lshlrev_b32_e32 v200, 16, v192
	v_and_b32_e32 v201, 0xffff0000, v192
	v_lshlrev_b32_e32 v202, 16, v193
	v_and_b32_e32 v203, 0xffff0000, v193
	v_pk_mul_f32 v[110:111], v[110:111], v[202:203]
	v_pk_mul_f32 v[108:109], v[108:109], v[200:201]
	global_store_dwordx4 v219, v[108:111], s[6:7] offset:0
	s_waitcnt vmcnt(7)
	v_lshlrev_b32_e32 v204, 16, v194
	v_and_b32_e32 v205, 0xffff0000, v194
	v_lshlrev_b32_e32 v206, 16, v195
	v_and_b32_e32 v207, 0xffff0000, v195
	v_pk_mul_f32 v[106:107], v[106:107], v[206:207]
	v_pk_mul_f32 v[104:105], v[104:105], v[204:205]
	global_store_dwordx4 v219, v[104:107], s[6:7] offset:64
	s_waitcnt vmcnt(7)
	v_lshlrev_b32_e32 v200, 16, v196
	v_and_b32_e32 v201, 0xffff0000, v196
	v_lshlrev_b32_e32 v202, 16, v197
	v_and_b32_e32 v203, 0xffff0000, v197
	v_pk_mul_f32 v[102:103], v[102:103], v[202:203]
	v_pk_mul_f32 v[100:101], v[100:101], v[200:201]
	global_store_dwordx4 v219, v[100:103], s[6:7] offset:512
	s_waitcnt vmcnt(7)
	v_lshlrev_b32_e32 v204, 16, v198
	v_and_b32_e32 v205, 0xffff0000, v198
	v_lshlrev_b32_e32 v206, 16, v199
	v_and_b32_e32 v207, 0xffff0000, v199
	v_pk_mul_f32 v[98:99], v[98:99], v[206:207]
	v_pk_mul_f32 v[96:97], v[96:97], v[204:205]
	global_store_dwordx4 v219, v[96:99], s[6:7] offset:576
	v_add_u32_e32 v216, 0x80000, v220
	v_add_u32_e32 v218, 0x20000, v221
	v_add_u32_e32 v217, 0xc0000, v220
	v_add_u32_e32 v219, 0x30000, v221
	global_load_dwordx2 v[184:185], v216, s[82:83] offset:0
	global_load_dwordx2 v[186:187], v216, s[82:83] offset:32
	global_load_dwordx2 v[188:189], v216, s[82:83] offset:256
	global_load_dwordx2 v[190:191], v216, s[82:83] offset:288
	global_load_dwordx2 v[192:193], v217, s[82:83] offset:0
	global_load_dwordx2 v[194:195], v217, s[82:83] offset:32
	global_load_dwordx2 v[196:197], v217, s[82:83] offset:256
	global_load_dwordx2 v[198:199], v217, s[82:83] offset:288
	s_waitcnt vmcnt(7)
	v_lshlrev_b32_e32 v200, 16, v184
	v_and_b32_e32 v201, 0xffff0000, v184
	v_lshlrev_b32_e32 v202, 16, v185
	v_and_b32_e32 v203, 0xffff0000, v185
	v_pk_mul_f32 v[94:95], v[94:95], v[202:203]
	v_pk_mul_f32 v[92:93], v[92:93], v[200:201]
	global_store_dwordx4 v218, v[92:95], s[6:7] offset:0
	s_waitcnt vmcnt(7)
	v_lshlrev_b32_e32 v204, 16, v186
	v_and_b32_e32 v205, 0xffff0000, v186
	v_lshlrev_b32_e32 v206, 16, v187
	v_and_b32_e32 v207, 0xffff0000, v187
	v_pk_mul_f32 v[90:91], v[90:91], v[206:207]
	v_pk_mul_f32 v[88:89], v[88:89], v[204:205]
	global_store_dwordx4 v218, v[88:91], s[6:7] offset:64
	s_waitcnt vmcnt(7)
	v_lshlrev_b32_e32 v200, 16, v188
	v_and_b32_e32 v201, 0xffff0000, v188
	v_lshlrev_b32_e32 v202, 16, v189
	v_and_b32_e32 v203, 0xffff0000, v189
	v_pk_mul_f32 v[86:87], v[86:87], v[202:203]
	v_pk_mul_f32 v[84:85], v[84:85], v[200:201]
	global_store_dwordx4 v218, v[84:87], s[6:7] offset:512
	s_waitcnt vmcnt(7)
	v_lshlrev_b32_e32 v204, 16, v190
	v_and_b32_e32 v205, 0xffff0000, v190
	v_lshlrev_b32_e32 v206, 16, v191
	v_and_b32_e32 v207, 0xffff0000, v191
	v_pk_mul_f32 v[82:83], v[82:83], v[206:207]
	v_pk_mul_f32 v[80:81], v[80:81], v[204:205]
	global_store_dwordx4 v218, v[80:83], s[6:7] offset:576
	s_waitcnt vmcnt(7)
	v_lshlrev_b32_e32 v200, 16, v192
	v_and_b32_e32 v201, 0xffff0000, v192
	v_lshlrev_b32_e32 v202, 16, v193
	v_and_b32_e32 v203, 0xffff0000, v193
	v_pk_mul_f32 v[78:79], v[78:79], v[202:203]
	v_pk_mul_f32 v[76:77], v[76:77], v[200:201]
	global_store_dwordx4 v219, v[76:79], s[6:7] offset:0
	s_waitcnt vmcnt(7)
; __device__ __forceinline__ float bflo(unsigned w) { return __uint_as_float(w << 16); }
; __device__ __forceinline__ float bfhi(unsigned w) { return __uint_as_float(w & 0xffff0000u); }
;     __device__ __forceinline__ void operator()(const f32x4 (&acc)[2][2][4][2], const pg8::Unit& u, int wr, int wc, int fr, int fq) const {
;         const int row0 = u.pm * 256 + wr * 64 + fr, col0 = u.pn * 256 + wc * 32 + 4 * fq;
; #pragma unroll
;         for (int ai = 0; ai < 2; ++ai)
; #pragma unroll
;             for (int m = 0; m < 4; ++m) { const size_t r = (size_t)(row0 + ai * 128 + m * 16);
; #pragma unroll
;                 for (int bj = 0; bj < 2; ++bj)
; #pragma unroll
;                     for (int n = 0; n < 2; ++n) { const int c = col0 + bj * 128 + n * 16;
;                         const u32x2 g = *(const u32x2*)(PROJ + r * 8192 + 6144 + c);
;                         const f32x4 s = (f32x4){bflo(g.x), bfhi(g.x), bflo(g.y), bfhi(g.y)};
;                         *(f32x4*)(MT + r * 1024 + c) = acc[ai][bj][m][n] * s; } }
	v_lshlrev_b32_e32 v204, 16, v194
	v_and_b32_e32 v205, 0xffff0000, v194
	v_lshlrev_b32_e32 v206, 16, v195
	v_and_b32_e32 v207, 0xffff0000, v195
	v_pk_mul_f32 v[74:75], v[74:75], v[206:207]
	v_pk_mul_f32 v[72:73], v[72:73], v[204:205]
	global_store_dwordx4 v219, v[72:75], s[6:7] offset:64
	s_waitcnt vmcnt(7)
	v_lshlrev_b32_e32 v200, 16, v196
	v_and_b32_e32 v201, 0xffff0000, v196
	v_lshlrev_b32_e32 v202, 16, v197
	v_and_b32_e32 v203, 0xffff0000, v197
	v_pk_mul_f32 v[70:71], v[70:71], v[202:203]
	v_pk_mul_f32 v[68:69], v[68:69], v[200:201]
	global_store_dwordx4 v219, v[68:71], s[6:7] offset:512
	s_waitcnt vmcnt(7)
	v_lshlrev_b32_e32 v204, 16, v198
	v_and_b32_e32 v205, 0xffff0000, v198
	v_lshlrev_b32_e32 v206, 16, v199
	v_and_b32_e32 v207, 0xffff0000, v199
	v_pk_mul_f32 v[66:67], v[66:67], v[206:207]
	v_pk_mul_f32 v[64:65], v[64:65], v[204:205]
	global_store_dwordx4 v219, v[64:67], s[6:7] offset:576
	v_add_u32_e32 v216, 0x200000, v220
	v_add_u32_e32 v218, 0x80000, v221
	v_add_u32_e32 v217, 0x240000, v220
	v_add_u32_e32 v219, 0x90000, v221
	global_load_dwordx2 v[184:185], v216, s[82:83] offset:0
	global_load_dwordx2 v[186:187], v216, s[82:83] offset:32
	global_load_dwordx2 v[188:189], v216, s[82:83] offset:256
	global_load_dwordx2 v[190:191], v216, s[82:83] offset:288
	global_load_dwordx2 v[192:193], v217, s[82:83] offset:0
	global_load_dwordx2 v[194:195], v217, s[82:83] offset:32
	global_load_dwordx2 v[196:197], v217, s[82:83] offset:256
	global_load_dwordx2 v[198:199], v217, s[82:83] offset:288
	s_waitcnt vmcnt(7)
	v_lshlrev_b32_e32 v200, 16, v184
	v_and_b32_e32 v201, 0xffff0000, v184
	v_lshlrev_b32_e32 v202, 16, v185
	v_and_b32_e32 v203, 0xffff0000, v185
	v_pk_mul_f32 v[62:63], v[62:63], v[202:203]
	v_pk_mul_f32 v[60:61], v[60:61], v[200:201]
	global_store_dwordx4 v218, v[60:63], s[6:7] offset:0
	s_waitcnt vmcnt(7)
	v_lshlrev_b32_e32 v204, 16, v186
	v_and_b32_e32 v205, 0xffff0000, v186
	v_lshlrev_b32_e32 v206, 16, v187
	v_and_b32_e32 v207, 0xffff0000, v187
	v_pk_mul_f32 v[58:59], v[58:59], v[206:207]
	v_pk_mul_f32 v[56:57], v[56:57], v[204:205]
	global_store_dwordx4 v218, v[56:59], s[6:7] offset:64
	s_waitcnt vmcnt(7)
	v_lshlrev_b32_e32 v200, 16, v188
	v_and_b32_e32 v201, 0xffff0000, v188
	v_lshlrev_b32_e32 v202, 16, v189
	v_and_b32_e32 v203, 0xffff0000, v189
	v_pk_mul_f32 v[54:55], v[54:55], v[202:203]
	v_pk_mul_f32 v[52:53], v[52:53], v[200:201]
	global_store_dwordx4 v218, v[52:55], s[6:7] offset:512
	s_waitcnt vmcnt(7)
	v_lshlrev_b32_e32 v204, 16, v190
	v_and_b32_e32 v205, 0xffff0000, v190
	v_lshlrev_b32_e32 v206, 16, v191
	v_and_b32_e32 v207, 0xffff0000, v191
	v_pk_mul_f32 v[50:51], v[50:51], v[206:207]
	v_pk_mul_f32 v[48:49], v[48:49], v[204:205]
	global_store_dwordx4 v218, v[48:51], s[6:7] offset:576
	s_waitcnt vmcnt(7)
	v_lshlrev_b32_e32 v200, 16, v192
	v_and_b32_e32 v201, 0xffff0000, v192
	v_lshlrev_b32_e32 v202, 16, v193
	v_and_b32_e32 v203, 0xffff0000, v193
	v_pk_mul_f32 v[46:47], v[46:47], v[202:203]
	v_pk_mul_f32 v[44:45], v[44:45], v[200:201]
	global_store_dwordx4 v219, v[44:47], s[6:7] offset:0
	s_waitcnt vmcnt(7)
	v_lshlrev_b32_e32 v204, 16, v194
	v_and_b32_e32 v205, 0xffff0000, v194
	v_lshlrev_b32_e32 v206, 16, v195
	v_and_b32_e32 v207, 0xffff0000, v195
	v_pk_mul_f32 v[42:43], v[42:43], v[206:207]
	v_pk_mul_f32 v[40:41], v[40:41], v[204:205]
	global_store_dwordx4 v219, v[40:43], s[6:7] offset:64
	s_waitcnt vmcnt(7)
	v_lshlrev_b32_e32 v200, 16, v196
	v_and_b32_e32 v201, 0xffff0000, v196
	v_lshlrev_b32_e32 v202, 16, v197
	v_and_b32_e32 v203, 0xffff0000, v197
	v_pk_mul_f32 v[38:39], v[38:39], v[202:203]
	v_pk_mul_f32 v[36:37], v[36:37], v[200:201]
	global_store_dwordx4 v219, v[36:39], s[6:7] offset:512
	s_waitcnt vmcnt(7)
; __device__ __forceinline__ float bflo(unsigned w) { return __uint_as_float(w << 16); }
; __device__ __forceinline__ float bfhi(unsigned w) { return __uint_as_float(w & 0xffff0000u); }
;     __device__ __forceinline__ void operator()(const f32x4 (&acc)[2][2][4][2], const pg8::Unit& u, int wr, int wc, int fr, int fq) const {
;         const int row0 = u.pm * 256 + wr * 64 + fr, col0 = u.pn * 256 + wc * 32 + 4 * fq;
; #pragma unroll
;         for (int ai = 0; ai < 2; ++ai)
; #pragma unroll
;             for (int m = 0; m < 4; ++m) { const size_t r = (size_t)(row0 + ai * 128 + m * 16);
; #pragma unroll
;                 for (int bj = 0; bj < 2; ++bj)
; #pragma unroll
;                     for (int n = 0; n < 2; ++n) { const int c = col0 + bj * 128 + n * 16;
;                         const u32x2 g = *(const u32x2*)(PROJ + r * 8192 + 6144 + c);
;                         const f32x4 s = (f32x4){bflo(g.x), bfhi(g.x), bflo(g.y), bfhi(g.y)};
;                         *(f32x4*)(MT + r * 1024 + c) = acc[ai][bj][m][n] * s; } }
	v_lshlrev_b32_e32 v204, 16, v198
	v_and_b32_e32 v205, 0xffff0000, v198
	v_lshlrev_b32_e32 v206, 16, v199
	v_and_b32_e32 v207, 0xffff0000, v199
	v_pk_mul_f32 v[34:35], v[34:35], v[206:207]
	v_pk_mul_f32 v[32:33], v[32:33], v[204:205]
	global_store_dwordx4 v219, v[32:35], s[6:7] offset:576
	v_add_u32_e32 v216, 0x280000, v220
	v_add_u32_e32 v218, 0xa0000, v221
	v_add_u32_e32 v217, 0x2c0000, v220
	v_add_u32_e32 v219, 0xb0000, v221
	global_load_dwordx2 v[184:185], v216, s[82:83] offset:0
	global_load_dwordx2 v[186:187], v216, s[82:83] offset:32
	global_load_dwordx2 v[188:189], v216, s[82:83] offset:256
	global_load_dwordx2 v[190:191], v216, s[82:83] offset:288
	global_load_dwordx2 v[192:193], v217, s[82:83] offset:0
	global_load_dwordx2 v[194:195], v217, s[82:83] offset:32
	global_load_dwordx2 v[196:197], v217, s[82:83] offset:256
	global_load_dwordx2 v[198:199], v217, s[82:83] offset:288
	s_waitcnt vmcnt(7)
	v_lshlrev_b32_e32 v200, 16, v184
	v_and_b32_e32 v201, 0xffff0000, v184
	v_lshlrev_b32_e32 v202, 16, v185
	v_and_b32_e32 v203, 0xffff0000, v185
	v_pk_mul_f32 v[30:31], v[30:31], v[202:203]
	v_pk_mul_f32 v[28:29], v[28:29], v[200:201]
	global_store_dwordx4 v218, v[28:31], s[6:7] offset:0
	s_waitcnt vmcnt(7)
	v_lshlrev_b32_e32 v204, 16, v186
	v_and_b32_e32 v205, 0xffff0000, v186
	v_lshlrev_b32_e32 v206, 16, v187
	v_and_b32_e32 v207, 0xffff0000, v187
	v_pk_mul_f32 v[26:27], v[26:27], v[206:207]
	v_pk_mul_f32 v[24:25], v[24:25], v[204:205]
	global_store_dwordx4 v218, v[24:27], s[6:7] offset:64
	s_waitcnt vmcnt(7)
	v_lshlrev_b32_e32 v200, 16, v188
	v_and_b32_e32 v201, 0xffff0000, v188
	v_lshlrev_b32_e32 v202, 16, v189
	v_and_b32_e32 v203, 0xffff0000, v189
	v_pk_mul_f32 v[22:23], v[22:23], v[202:203]
	v_pk_mul_f32 v[20:21], v[20:21], v[200:201]
	global_store_dwordx4 v218, v[20:23], s[6:7] offset:512
	s_waitcnt vmcnt(7)
	v_lshlrev_b32_e32 v204, 16, v190
	v_and_b32_e32 v205, 0xffff0000, v190
	v_lshlrev_b32_e32 v206, 16, v191
	v_and_b32_e32 v207, 0xffff0000, v191
	v_pk_mul_f32 v[18:19], v[18:19], v[206:207]
	v_pk_mul_f32 v[16:17], v[16:17], v[204:205]
	global_store_dwordx4 v218, v[16:19], s[6:7] offset:576
	s_waitcnt vmcnt(7)
	v_lshlrev_b32_e32 v200, 16, v192
	v_and_b32_e32 v201, 0xffff0000, v192
	v_lshlrev_b32_e32 v202, 16, v193
	v_and_b32_e32 v203, 0xffff0000, v193
	v_pk_mul_f32 v[14:15], v[14:15], v[202:203]
	v_pk_mul_f32 v[12:13], v[12:13], v[200:201]
	global_store_dwordx4 v219, v[12:15], s[6:7] offset:0
	s_waitcnt vmcnt(7)
	v_lshlrev_b32_e32 v204, 16, v194
	v_and_b32_e32 v205, 0xffff0000, v194
	v_lshlrev_b32_e32 v206, 16, v195
	v_and_b32_e32 v207, 0xffff0000, v195
	v_pk_mul_f32 v[10:11], v[10:11], v[206:207]
	v_pk_mul_f32 v[8:9], v[8:9], v[204:205]
	global_store_dwordx4 v219, v[8:11], s[6:7] offset:64
	s_waitcnt vmcnt(7)
	v_lshlrev_b32_e32 v200, 16, v196
	v_and_b32_e32 v201, 0xffff0000, v196
	v_lshlrev_b32_e32 v202, 16, v197
	v_and_b32_e32 v203, 0xffff0000, v197
	v_pk_mul_f32 v[6:7], v[6:7], v[202:203]
	v_pk_mul_f32 v[4:5], v[4:5], v[200:201]
	global_store_dwordx4 v219, v[4:7], s[6:7] offset:512
	s_waitcnt vmcnt(7)
	v_lshlrev_b32_e32 v204, 16, v198
	v_and_b32_e32 v205, 0xffff0000, v198
	v_lshlrev_b32_e32 v206, 16, v199
	v_and_b32_e32 v207, 0xffff0000, v199
	v_pk_mul_f32 v[2:3], v[2:3], v[206:207]
	v_pk_mul_f32 v[0:1], v[0:1], v[204:205]
	global_store_dwordx4 v219, v[0:3], s[6:7] offset:576
	s_and_b64 vcc, exec, s[42:43]
	s_nop 4
	s_mov_b64 s[6:7], -1
	s_cbranch_vccnz .LBB0_313
	s_andn2_b64 vcc, exec, s[26:27]
	s_cbranch_vccnz .LBB0_312
	s_barrier
	s_branch .LBB0_312
